# early-flush timing: 24th-of-32 arriver (instead of 20th) issues the early buffer_wbl2 at the five global barriers
# speedup vs baseline: 1.0059x; 1.0030x over previous
; __device__ __forceinline__ unsigned xb_ld(unsigned* p)              { return __hip_atomic_load(p, __ATOMIC_RELAXED, __HIP_MEMORY_SCOPE_AGENT); }
; __device__ __forceinline__ unsigned xb_add(unsigned* p, unsigned v) { return __hip_atomic_fetch_add(p, v, __ATOMIC_RELAXED, __HIP_MEMORY_SCOPE_AGENT); }
; #define XB_SPIN(cond, bar) do { unsigned _sp = 0; while (cond) { __builtin_amdgcn_s_sleep(1); \
;     if ((++_sp & 255u) == 0u) { if (xb_ld(&(bar)[XB_TMO])) break; if (_sp > XB_SPIN_CAP) { atomicAdd(&(bar)[XB_TMO], 1u); break; } } } } while (0)
; __device__ __forceinline__ void xcd_barrier(const XcdBarrier& b) {
;     ...
;         const unsigned old = xb_add(&bar[XB_XSUB(b.x)], 1u);
;         const unsigned gen = old / nloc;
;         if (old + 1u == (gen + 1u) * nloc) {
;             __builtin_amdgcn_fence(__ATOMIC_RELEASE, "agent");
;             asm volatile("s_waitcnt vmcnt(0)" ::: "memory");
;             const unsigned og = xb_add(&bar[XB_TOP], 1u);
;             const unsigned tg = og / nx;
;             if (og + 1u == (tg + 1u) * nx) xb_add(&bar[XB_TOPGEN], 1u);
;             else XB_SPIN(xb_ld(&bar[XB_TOPGEN]) == tg, bar);
;             __builtin_amdgcn_fence(__ATOMIC_ACQUIRE, "agent");
;             xb_add(&bar[XB_XGEN(b.x)], 1u);
;             asm volatile("s_waitcnt vmcnt(0)" ::: "memory");
.Lgbar_mid_0:
	v_add_u32_e32 v3, 8, v3
	v_cmp_ne_u32_e32 vcc, v3, v5
	s_cbranch_vccnz .Lgbar_poll_0
	buffer_wbl2 sc1
	s_waitcnt vmcnt(0)
